# E20 + the 16 stores of the regenerated SwiGLU epilogue issued as global_store_dwordx4 (off) instead of flat_store_dwordx4
# speedup vs baseline: 1.0036x; 1.0036x over previous
; __device__ __forceinline__ unsigned cvt_pk_bf16(float lo, float hi) { unsigned r; asm volatile("v_cvt_pk_bf16_f32 %0, %1, %2" : "=v"(r) : "v"(lo), "v"(hi)); return r; }
; __device__ __forceinline__ float silu_mul(float g, float u) { return g * u * __builtin_amdgcn_rcpf(1.0f + __builtin_amdgcn_exp2f(-1.4426950408889634f * g)); }
;     __device__ __forceinline__ void operator()(const f32x4 (&acc)[2][2][4][2], const Unit& u, int wr, int wc, int fr, int fq) const {
;         const int row0 = u.pm * BM + wr * 64 + fr, col0 = u.pn * HALF + wc * 32 + 8 * fq;
; #pragma unroll
;         for (int ai = 0; ai < 2; ++ai)
; #pragma unroll
;             for (int m = 0; m < 4; ++m) { bf16_t* rowp = O + (size_t)(row0 + ai * HALF + m * 16) * ldc + col0;
;                 const f32x4 g0 = acc[ai][0][m][0], g1 = acc[ai][0][m][1], u0 = acc[ai][1][m][0], u1 = acc[ai][1][m][1];
;                 u32x4 w; w.x = cvt_pk_bf16(silu_mul(g0[0], u0[0]), silu_mul(g0[1], u0[1])); w.y = cvt_pk_bf16(silu_mul(g0[2], u0[2]), silu_mul(g0[3], u0[3]));
;                 w.z = cvt_pk_bf16(silu_mul(g1[0], u1[0]), silu_mul(g1[1], u1[1])); w.w = cvt_pk_bf16(silu_mul(g1[2], u1[2]), silu_mul(g1[3], u1[3]));
;                 *(u32x4*)rowp = w; }
.LBB0_127:
	v_mov_b32_e32 v228, 0xbfb8aa3b
	v_mov_b32_e32 v229, 0xbfb8aa3b
	v_mov_b32_e32 v230, 1.0
	v_mov_b32_e32 v231, 1.0
	v_lshl_or_b32 v144, s44, 7, v150
	v_lshl_add_u32 v154, s18, 8, v148
	v_ashrrev_i32_e32 v145, 31, v144
	v_mov_b64_e32 v[146:147], s[4:5]
	v_lshlrev_b64 v[144:145], 1, v[144:145]
	v_mad_i64_i32 v[236:237], s[20:21], v154, s43, v[146:147]
	v_pk_mul_f32 v[240:241], v[124:125], v[228:229]
	v_pk_mul_f32 v[242:243], v[126:127], v[228:229]
	v_pk_mul_f32 v[244:245], v[116:117], v[228:229]
	v_pk_mul_f32 v[246:247], v[118:119], v[228:229]
	v_lshl_add_u64 v[236:237], v[236:237], 0, v[144:145]
	v_exp_f32_e32 v240, v240
	v_exp_f32_e32 v241, v241
	v_exp_f32_e32 v242, v242
	v_exp_f32_e32 v243, v243
	v_exp_f32_e32 v244, v244
	v_exp_f32_e32 v245, v245
	v_exp_f32_e32 v246, v246
	v_exp_f32_e32 v247, v247
	v_pk_mul_f32 v[120:121], v[124:125], v[120:121]
	v_pk_mul_f32 v[122:123], v[126:127], v[122:123]
	v_pk_mul_f32 v[112:113], v[116:117], v[112:113]
	v_pk_mul_f32 v[114:115], v[118:119], v[114:115]
	v_pk_add_f32 v[240:241], v[240:241], v[230:231]
	v_pk_add_f32 v[242:243], v[242:243], v[230:231]
	v_pk_add_f32 v[244:245], v[244:245], v[230:231]
	v_pk_add_f32 v[246:247], v[246:247], v[230:231]
	v_rcp_f32_e32 v240, v240
	v_rcp_f32_e32 v241, v241
	v_rcp_f32_e32 v242, v242
	v_rcp_f32_e32 v243, v243
	v_rcp_f32_e32 v244, v244
	v_rcp_f32_e32 v245, v245
	v_rcp_f32_e32 v246, v246
	v_rcp_f32_e32 v247, v247
	v_pk_mul_f32 v[120:121], v[120:121], v[240:241]
	v_pk_mul_f32 v[122:123], v[122:123], v[242:243]
	v_pk_mul_f32 v[112:113], v[112:113], v[244:245]
	v_pk_mul_f32 v[114:115], v[114:115], v[246:247]
	v_cvt_pk_bf16_f32 v232, v120, v121
	v_cvt_pk_bf16_f32 v233, v122, v123
	v_cvt_pk_bf16_f32 v234, v112, v113
	v_cvt_pk_bf16_f32 v235, v114, v115
	global_store_dwordx4 v[236:237], v[232:235], off
	v_or_b32_e32 v238, 16, v154
	v_mad_i64_i32 v[236:237], s[20:21], v238, s43, v[146:147]
	v_pk_mul_f32 v[240:241], v[108:109], v[228:229]
	v_pk_mul_f32 v[242:243], v[110:111], v[228:229]
	v_pk_mul_f32 v[244:245], v[100:101], v[228:229]
	v_pk_mul_f32 v[246:247], v[102:103], v[228:229]
	v_lshl_add_u64 v[236:237], v[236:237], 0, v[144:145]
	v_exp_f32_e32 v240, v240
	v_exp_f32_e32 v241, v241
	v_exp_f32_e32 v242, v242
	v_exp_f32_e32 v243, v243
	v_exp_f32_e32 v244, v244
	v_exp_f32_e32 v245, v245
	v_exp_f32_e32 v246, v246
	v_exp_f32_e32 v247, v247
	v_pk_mul_f32 v[104:105], v[108:109], v[104:105]
	v_pk_mul_f32 v[106:107], v[110:111], v[106:107]
	v_pk_mul_f32 v[96:97], v[100:101], v[96:97]
	v_pk_mul_f32 v[98:99], v[102:103], v[98:99]
	v_pk_add_f32 v[240:241], v[240:241], v[230:231]
	v_pk_add_f32 v[242:243], v[242:243], v[230:231]
	v_pk_add_f32 v[244:245], v[244:245], v[230:231]
	v_pk_add_f32 v[246:247], v[246:247], v[230:231]
	v_rcp_f32_e32 v240, v240
	v_rcp_f32_e32 v241, v241
	v_rcp_f32_e32 v242, v242
	v_rcp_f32_e32 v243, v243
	v_rcp_f32_e32 v244, v244
	v_rcp_f32_e32 v245, v245
	v_rcp_f32_e32 v246, v246
	v_rcp_f32_e32 v247, v247
	v_pk_mul_f32 v[104:105], v[104:105], v[240:241]
	v_pk_mul_f32 v[106:107], v[106:107], v[242:243]
	v_pk_mul_f32 v[96:97], v[96:97], v[244:245]
	v_pk_mul_f32 v[98:99], v[98:99], v[246:247]
	v_cvt_pk_bf16_f32 v232, v104, v105
	v_cvt_pk_bf16_f32 v233, v106, v107
	v_cvt_pk_bf16_f32 v234, v96, v97
	v_cvt_pk_bf16_f32 v235, v98, v99
	global_store_dwordx4 v[236:237], v[232:235], off
	v_or_b32_e32 v238, 32, v154
	v_mad_i64_i32 v[236:237], s[20:21], v238, s43, v[146:147]
	v_pk_mul_f32 v[240:241], v[92:93], v[228:229]
	v_pk_mul_f32 v[242:243], v[94:95], v[228:229]
	v_pk_mul_f32 v[244:245], v[84:85], v[228:229]
	v_pk_mul_f32 v[246:247], v[86:87], v[228:229]
	v_lshl_add_u64 v[236:237], v[236:237], 0, v[144:145]
	v_exp_f32_e32 v240, v240
	v_exp_f32_e32 v241, v241
	v_exp_f32_e32 v242, v242
	v_exp_f32_e32 v243, v243
	v_exp_f32_e32 v244, v244
	v_exp_f32_e32 v245, v245
	v_exp_f32_e32 v246, v246
	v_exp_f32_e32 v247, v247
	v_pk_mul_f32 v[88:89], v[92:93], v[88:89]
	v_pk_mul_f32 v[90:91], v[94:95], v[90:91]
	v_pk_mul_f32 v[80:81], v[84:85], v[80:81]
	v_pk_mul_f32 v[82:83], v[86:87], v[82:83]
	v_pk_add_f32 v[240:241], v[240:241], v[230:231]
	v_pk_add_f32 v[242:243], v[242:243], v[230:231]
	v_pk_add_f32 v[244:245], v[244:245], v[230:231]
	v_pk_add_f32 v[246:247], v[246:247], v[230:231]
	v_rcp_f32_e32 v240, v240
	v_rcp_f32_e32 v241, v241
	v_rcp_f32_e32 v242, v242
	v_rcp_f32_e32 v243, v243
	v_rcp_f32_e32 v244, v244
	v_rcp_f32_e32 v245, v245
	v_rcp_f32_e32 v246, v246
	v_rcp_f32_e32 v247, v247
	v_pk_mul_f32 v[88:89], v[88:89], v[240:241]
	v_pk_mul_f32 v[90:91], v[90:91], v[242:243]
	v_pk_mul_f32 v[80:81], v[80:81], v[244:245]
	v_pk_mul_f32 v[82:83], v[82:83], v[246:247]
	v_cvt_pk_bf16_f32 v232, v88, v89
	v_cvt_pk_bf16_f32 v233, v90, v91
	v_cvt_pk_bf16_f32 v234, v80, v81
	v_cvt_pk_bf16_f32 v235, v82, v83
	global_store_dwordx4 v[236:237], v[232:235], off
	v_or_b32_e32 v238, 48, v154
	v_mad_i64_i32 v[236:237], s[20:21], v238, s43, v[146:147]
	v_pk_mul_f32 v[240:241], v[76:77], v[228:229]
	v_pk_mul_f32 v[242:243], v[78:79], v[228:229]
	v_pk_mul_f32 v[244:245], v[68:69], v[228:229]
	v_pk_mul_f32 v[246:247], v[70:71], v[228:229]
	v_lshl_add_u64 v[236:237], v[236:237], 0, v[144:145]
	v_exp_f32_e32 v240, v240
	v_exp_f32_e32 v241, v241
	v_exp_f32_e32 v242, v242
	v_exp_f32_e32 v243, v243
	v_exp_f32_e32 v244, v244
	v_exp_f32_e32 v245, v245
	v_exp_f32_e32 v246, v246
	v_exp_f32_e32 v247, v247
	v_pk_mul_f32 v[72:73], v[76:77], v[72:73]
	v_pk_mul_f32 v[74:75], v[78:79], v[74:75]
	v_pk_mul_f32 v[64:65], v[68:69], v[64:65]
	v_pk_mul_f32 v[66:67], v[70:71], v[66:67]
	v_pk_add_f32 v[240:241], v[240:241], v[230:231]
	v_pk_add_f32 v[242:243], v[242:243], v[230:231]
	v_pk_add_f32 v[244:245], v[244:245], v[230:231]
; __device__ __forceinline__ unsigned cvt_pk_bf16(float lo, float hi) { unsigned r; asm volatile("v_cvt_pk_bf16_f32 %0, %1, %2" : "=v"(r) : "v"(lo), "v"(hi)); return r; }
; #define PG8_BAR __builtin_amdgcn_s_barrier()
; __device__ __forceinline__ float silu_mul(float g, float u) { return g * u * __builtin_amdgcn_rcpf(1.0f + __builtin_amdgcn_exp2f(-1.4426950408889634f * g)); }
;     __device__ __forceinline__ void operator()(const f32x4 (&acc)[2][2][4][2], const Unit& u, int wr, int wc, int fr, int fq) const {
;         const int row0 = u.pm * BM + wr * 64 + fr, col0 = u.pn * HALF + wc * 32 + 8 * fq;
; #pragma unroll
;         for (int ai = 0; ai < 2; ++ai)
; #pragma unroll
;             for (int m = 0; m < 4; ++m) { bf16_t* rowp = O + (size_t)(row0 + ai * HALF + m * 16) * ldc + col0;
;                 const f32x4 g0 = acc[ai][0][m][0], g1 = acc[ai][0][m][1], u0 = acc[ai][1][m][0], u1 = acc[ai][1][m][1];
;                 u32x4 w; w.x = cvt_pk_bf16(silu_mul(g0[0], u0[0]), silu_mul(g0[1], u0[1])); w.y = cvt_pk_bf16(silu_mul(g0[2], u0[2]), silu_mul(g0[3], u0[3]));
;                 w.z = cvt_pk_bf16(silu_mul(g1[0], u1[0]), silu_mul(g1[1], u1[1])); w.w = cvt_pk_bf16(silu_mul(g1[2], u1[2]), silu_mul(g1[3], u1[3]));
;                 *(u32x4*)rowp = w; }
; template <class Epi, class Sched, bool ALIGN_EPI = false, bool SP2 = false>
; __device__ __forceinline__ void gemm_phase(PG8_LAS unsigned char* lds, const Gemm g, const Sched& S, const Epi& E) {
;     ...
;         if constexpr (ALIGN_EPI) { if (wr == 0) PG8_BAR; }
;         if constexpr (!Epi::AFTER_DRAIN) { E(acc, cur, wr, wc, fr, fq); S.done(cur); }
;         if (!has_next) break;
; #pragma unroll
;         for (int a = 0; a < 2; ++a)
; #pragma unroll
;             for (int b = 0; b < 2; ++b)
; #pragma unroll
;                 for (int m = 0; m < 4; ++m)
; #pragma unroll
;                     for (int n = 0; n < 2; ++n) acc[a][b][m][n] = (f32x4){0.f, 0.f, 0.f, 0.f};
;         cur = nxt; cA = nA; cB = nB; ++ui;
;         if constexpr (ALIGN_EPI) { if (wr == 1) PG8_BAR; }
	v_pk_add_f32 v[246:247], v[246:247], v[230:231]
	v_rcp_f32_e32 v240, v240
	v_rcp_f32_e32 v241, v241
	v_rcp_f32_e32 v242, v242
	v_rcp_f32_e32 v243, v243
	v_rcp_f32_e32 v244, v244
	v_rcp_f32_e32 v245, v245
	v_rcp_f32_e32 v246, v246
	v_rcp_f32_e32 v247, v247
	v_pk_mul_f32 v[72:73], v[72:73], v[240:241]
	v_pk_mul_f32 v[74:75], v[74:75], v[242:243]
	v_pk_mul_f32 v[64:65], v[64:65], v[244:245]
	v_pk_mul_f32 v[66:67], v[66:67], v[246:247]
	v_cvt_pk_bf16_f32 v232, v72, v73
	v_cvt_pk_bf16_f32 v233, v74, v75
	v_cvt_pk_bf16_f32 v234, v64, v65
	v_cvt_pk_bf16_f32 v235, v66, v67
	global_store_dwordx4 v[236:237], v[232:235], off
	v_add_u32_e32 v238, 0x80, v154
	v_mad_i64_i32 v[236:237], s[20:21], v238, s43, v[146:147]
	v_pk_mul_f32 v[240:241], v[60:61], v[228:229]
	v_pk_mul_f32 v[242:243], v[62:63], v[228:229]
	v_pk_mul_f32 v[244:245], v[52:53], v[228:229]
	v_pk_mul_f32 v[246:247], v[54:55], v[228:229]
	v_lshl_add_u64 v[236:237], v[236:237], 0, v[144:145]
	v_exp_f32_e32 v240, v240
	v_exp_f32_e32 v241, v241
	v_exp_f32_e32 v242, v242
	v_exp_f32_e32 v243, v243
	v_exp_f32_e32 v244, v244
	v_exp_f32_e32 v245, v245
	v_exp_f32_e32 v246, v246
	v_exp_f32_e32 v247, v247
	v_pk_mul_f32 v[56:57], v[60:61], v[56:57]
	v_pk_mul_f32 v[58:59], v[62:63], v[58:59]
	v_pk_mul_f32 v[48:49], v[52:53], v[48:49]
	v_pk_mul_f32 v[50:51], v[54:55], v[50:51]
	v_pk_add_f32 v[240:241], v[240:241], v[230:231]
	v_pk_add_f32 v[242:243], v[242:243], v[230:231]
	v_pk_add_f32 v[244:245], v[244:245], v[230:231]
	v_pk_add_f32 v[246:247], v[246:247], v[230:231]
	v_rcp_f32_e32 v240, v240
	v_rcp_f32_e32 v241, v241
	v_rcp_f32_e32 v242, v242
	v_rcp_f32_e32 v243, v243
	v_rcp_f32_e32 v244, v244
	v_rcp_f32_e32 v245, v245
	v_rcp_f32_e32 v246, v246
	v_rcp_f32_e32 v247, v247
	v_pk_mul_f32 v[56:57], v[56:57], v[240:241]
	v_pk_mul_f32 v[58:59], v[58:59], v[242:243]
	v_pk_mul_f32 v[48:49], v[48:49], v[244:245]
	v_pk_mul_f32 v[50:51], v[50:51], v[246:247]
	v_cvt_pk_bf16_f32 v232, v56, v57
	v_cvt_pk_bf16_f32 v233, v58, v59
	v_cvt_pk_bf16_f32 v234, v48, v49
	v_cvt_pk_bf16_f32 v235, v50, v51
	global_store_dwordx4 v[236:237], v[232:235], off
	v_add_u32_e32 v238, 0x90, v154
	v_mad_i64_i32 v[236:237], s[20:21], v238, s43, v[146:147]
	v_pk_mul_f32 v[240:241], v[44:45], v[228:229]
	v_pk_mul_f32 v[242:243], v[46:47], v[228:229]
	v_pk_mul_f32 v[244:245], v[36:37], v[228:229]
	v_pk_mul_f32 v[246:247], v[38:39], v[228:229]
	v_lshl_add_u64 v[236:237], v[236:237], 0, v[144:145]
	v_exp_f32_e32 v240, v240
	v_exp_f32_e32 v241, v241
	v_exp_f32_e32 v242, v242
	v_exp_f32_e32 v243, v243
	v_exp_f32_e32 v244, v244
	v_exp_f32_e32 v245, v245
	v_exp_f32_e32 v246, v246
	v_exp_f32_e32 v247, v247
	v_pk_mul_f32 v[40:41], v[44:45], v[40:41]
	v_pk_mul_f32 v[42:43], v[46:47], v[42:43]
	v_pk_mul_f32 v[32:33], v[36:37], v[32:33]
	v_pk_mul_f32 v[34:35], v[38:39], v[34:35]
	v_pk_add_f32 v[240:241], v[240:241], v[230:231]
	v_pk_add_f32 v[242:243], v[242:243], v[230:231]
	v_pk_add_f32 v[244:245], v[244:245], v[230:231]
	v_pk_add_f32 v[246:247], v[246:247], v[230:231]
	v_rcp_f32_e32 v240, v240
	v_rcp_f32_e32 v241, v241
	v_rcp_f32_e32 v242, v242
	v_rcp_f32_e32 v243, v243
	v_rcp_f32_e32 v244, v244
	v_rcp_f32_e32 v245, v245
	v_rcp_f32_e32 v246, v246
	v_rcp_f32_e32 v247, v247
	v_pk_mul_f32 v[40:41], v[40:41], v[240:241]
	v_pk_mul_f32 v[42:43], v[42:43], v[242:243]
	v_pk_mul_f32 v[32:33], v[32:33], v[244:245]
	v_pk_mul_f32 v[34:35], v[34:35], v[246:247]
	v_cvt_pk_bf16_f32 v232, v40, v41
	v_cvt_pk_bf16_f32 v233, v42, v43
	v_cvt_pk_bf16_f32 v234, v32, v33
	v_cvt_pk_bf16_f32 v235, v34, v35
	global_store_dwordx4 v[236:237], v[232:235], off
	v_add_u32_e32 v238, 0xa0, v154
	v_mad_i64_i32 v[236:237], s[20:21], v238, s43, v[146:147]
	v_pk_mul_f32 v[240:241], v[28:29], v[228:229]
	v_pk_mul_f32 v[242:243], v[30:31], v[228:229]
	v_pk_mul_f32 v[244:245], v[20:21], v[228:229]
	v_pk_mul_f32 v[246:247], v[22:23], v[228:229]
	v_lshl_add_u64 v[236:237], v[236:237], 0, v[144:145]
	v_exp_f32_e32 v240, v240
	v_exp_f32_e32 v241, v241
	v_exp_f32_e32 v242, v242
	v_exp_f32_e32 v243, v243
	v_exp_f32_e32 v244, v244
	v_exp_f32_e32 v245, v245
	v_exp_f32_e32 v246, v246
	v_exp_f32_e32 v247, v247
	v_pk_mul_f32 v[24:25], v[28:29], v[24:25]
	v_pk_mul_f32 v[26:27], v[30:31], v[26:27]
	v_pk_mul_f32 v[16:17], v[20:21], v[16:17]
	v_pk_mul_f32 v[18:19], v[22:23], v[18:19]
	v_pk_add_f32 v[240:241], v[240:241], v[230:231]
	v_pk_add_f32 v[242:243], v[242:243], v[230:231]
	v_pk_add_f32 v[244:245], v[244:245], v[230:231]
	v_pk_add_f32 v[246:247], v[246:247], v[230:231]
	v_rcp_f32_e32 v240, v240
	v_rcp_f32_e32 v241, v241
	v_rcp_f32_e32 v242, v242
	v_rcp_f32_e32 v243, v243
	v_rcp_f32_e32 v244, v244
	v_rcp_f32_e32 v245, v245
	v_rcp_f32_e32 v246, v246
	v_rcp_f32_e32 v247, v247
	v_pk_mul_f32 v[24:25], v[24:25], v[240:241]
	v_pk_mul_f32 v[26:27], v[26:27], v[242:243]
	v_pk_mul_f32 v[16:17], v[16:17], v[244:245]
	v_pk_mul_f32 v[18:19], v[18:19], v[246:247]
	v_cvt_pk_bf16_f32 v232, v24, v25
	v_cvt_pk_bf16_f32 v233, v26, v27
	v_cvt_pk_bf16_f32 v234, v16, v17
	v_cvt_pk_bf16_f32 v235, v18, v19
	global_store_dwordx4 v[236:237], v[232:235], off
	v_add_u32_e32 v238, 0xb0, v154
	v_mad_i64_i32 v[236:237], s[20:21], v238, s43, v[146:147]
	v_pk_mul_f32 v[240:241], v[12:13], v[228:229]
	v_pk_mul_f32 v[242:243], v[14:15], v[228:229]
	v_pk_mul_f32 v[244:245], v[4:5], v[228:229]
	v_pk_mul_f32 v[246:247], v[6:7], v[228:229]
	v_lshl_add_u64 v[236:237], v[236:237], 0, v[144:145]
	v_exp_f32_e32 v240, v240
	v_exp_f32_e32 v241, v241
	v_exp_f32_e32 v242, v242
	v_exp_f32_e32 v243, v243
	v_exp_f32_e32 v244, v244
	v_exp_f32_e32 v245, v245
	v_exp_f32_e32 v246, v246
	v_exp_f32_e32 v247, v247
	v_pk_mul_f32 v[8:9], v[12:13], v[8:9]
	v_pk_mul_f32 v[10:11], v[14:15], v[10:11]
	v_pk_mul_f32 v[0:1], v[4:5], v[0:1]
	v_pk_mul_f32 v[2:3], v[6:7], v[2:3]
	v_pk_add_f32 v[240:241], v[240:241], v[230:231]
	v_pk_add_f32 v[242:243], v[242:243], v[230:231]
	v_pk_add_f32 v[244:245], v[244:245], v[230:231]
	v_pk_add_f32 v[246:247], v[246:247], v[230:231]
	v_rcp_f32_e32 v240, v240
	v_rcp_f32_e32 v241, v241
	v_rcp_f32_e32 v242, v242
	v_rcp_f32_e32 v243, v243
	v_rcp_f32_e32 v244, v244
	v_rcp_f32_e32 v245, v245
	v_rcp_f32_e32 v246, v246
	v_rcp_f32_e32 v247, v247
	v_pk_mul_f32 v[8:9], v[8:9], v[240:241]
	v_pk_mul_f32 v[10:11], v[10:11], v[242:243]
	v_pk_mul_f32 v[0:1], v[0:1], v[244:245]
	v_pk_mul_f32 v[2:3], v[2:3], v[246:247]
	v_cvt_pk_bf16_f32 v232, v8, v9
	v_cvt_pk_bf16_f32 v233, v10, v11
	v_cvt_pk_bf16_f32 v234, v0, v1
	v_cvt_pk_bf16_f32 v235, v2, v3
	global_store_dwordx4 v[236:237], v[232:235], off
	s_andn2_b64 vcc, exec, s[2:3]
	s_mov_b64 s[2:3], -1
	s_cbranch_vccnz .LBB0_116
	s_andn2_b64 vcc, exec, s[0:1]
	s_cbranch_vccnz .LBB0_115
	s_barrier
	s_branch .LBB0_115

; __device__ __forceinline__ unsigned cvt_pk_bf16(float lo, float hi) { unsigned r; asm volatile("v_cvt_pk_bf16_f32 %0, %1, %2" : "=v"(r) : "v"(lo), "v"(hi)); return r; }
; __device__ __forceinline__ float silu_mul(float g, float u) { return g * u * __builtin_amdgcn_rcpf(1.0f + __builtin_amdgcn_exp2f(-1.4426950408889634f * g)); }
;     __device__ __forceinline__ void operator()(const f32x4 (&acc)[2][2][4][2], const Unit& u, int wr, int wc, int fr, int fq) const {
;         const int row0 = u.pm * BM + wr * 64 + fr, col0 = u.pn * HALF + wc * 32 + 8 * fq;
; #pragma unroll
;         for (int ai = 0; ai < 2; ++ai)
; #pragma unroll
;             for (int m = 0; m < 4; ++m) { bf16_t* rowp = O + (size_t)(row0 + ai * HALF + m * 16) * ldc + col0;
;                 const f32x4 g0 = acc[ai][0][m][0], g1 = acc[ai][0][m][1], u0 = acc[ai][1][m][0], u1 = acc[ai][1][m][1];
;                 u32x4 w; w.x = cvt_pk_bf16(silu_mul(g0[0], u0[0]), silu_mul(g0[1], u0[1])); w.y = cvt_pk_bf16(silu_mul(g0[2], u0[2]), silu_mul(g0[3], u0[3]));
;                 w.z = cvt_pk_bf16(silu_mul(g1[0], u1[0]), silu_mul(g1[1], u1[1])); w.w = cvt_pk_bf16(silu_mul(g1[2], u1[2]), silu_mul(g1[3], u1[3]));
;                 *(u32x4*)rowp = w; }
.LBB0_1020:
	v_mov_b32_e32 v228, 0xbfb8aa3b
	v_mov_b32_e32 v229, 0xbfb8aa3b
	v_mov_b32_e32 v230, 1.0
	v_mov_b32_e32 v231, 1.0
	v_lshl_or_b32 v144, s45, 7, v150
	v_lshl_add_u32 v154, s20, 8, v148
	v_ashrrev_i32_e32 v145, 31, v144
	v_mov_b64_e32 v[146:147], s[6:7]
	v_lshlrev_b64 v[144:145], 1, v[144:145]
	v_mad_i64_i32 v[236:237], s[22:23], v154, s44, v[146:147]
	v_pk_mul_f32 v[240:241], v[124:125], v[228:229]
	v_pk_mul_f32 v[242:243], v[126:127], v[228:229]
	v_pk_mul_f32 v[244:245], v[116:117], v[228:229]
	v_pk_mul_f32 v[246:247], v[118:119], v[228:229]
	v_lshl_add_u64 v[236:237], v[236:237], 0, v[144:145]
	v_exp_f32_e32 v240, v240
	v_exp_f32_e32 v241, v241
	v_exp_f32_e32 v242, v242
	v_exp_f32_e32 v243, v243
	v_exp_f32_e32 v244, v244
	v_exp_f32_e32 v245, v245
	v_exp_f32_e32 v246, v246
	v_exp_f32_e32 v247, v247
	v_pk_mul_f32 v[120:121], v[124:125], v[120:121]
	v_pk_mul_f32 v[122:123], v[126:127], v[122:123]
	v_pk_mul_f32 v[112:113], v[116:117], v[112:113]
	v_pk_mul_f32 v[114:115], v[118:119], v[114:115]
	v_pk_add_f32 v[240:241], v[240:241], v[230:231]
	v_pk_add_f32 v[242:243], v[242:243], v[230:231]
	v_pk_add_f32 v[244:245], v[244:245], v[230:231]
	v_pk_add_f32 v[246:247], v[246:247], v[230:231]
	v_rcp_f32_e32 v240, v240
	v_rcp_f32_e32 v241, v241
	v_rcp_f32_e32 v242, v242
	v_rcp_f32_e32 v243, v243
	v_rcp_f32_e32 v244, v244
	v_rcp_f32_e32 v245, v245
	v_rcp_f32_e32 v246, v246
	v_rcp_f32_e32 v247, v247
	v_pk_mul_f32 v[120:121], v[120:121], v[240:241]
	v_pk_mul_f32 v[122:123], v[122:123], v[242:243]
	v_pk_mul_f32 v[112:113], v[112:113], v[244:245]
	v_pk_mul_f32 v[114:115], v[114:115], v[246:247]
	v_cvt_pk_bf16_f32 v232, v120, v121
	v_cvt_pk_bf16_f32 v233, v122, v123
	v_cvt_pk_bf16_f32 v234, v112, v113
	v_cvt_pk_bf16_f32 v235, v114, v115
	global_store_dwordx4 v[236:237], v[232:235], off
	v_or_b32_e32 v238, 16, v154
	v_mad_i64_i32 v[236:237], s[22:23], v238, s44, v[146:147]
	v_pk_mul_f32 v[240:241], v[108:109], v[228:229]
	v_pk_mul_f32 v[242:243], v[110:111], v[228:229]
	v_pk_mul_f32 v[244:245], v[100:101], v[228:229]
	v_pk_mul_f32 v[246:247], v[102:103], v[228:229]
	v_lshl_add_u64 v[236:237], v[236:237], 0, v[144:145]
	v_exp_f32_e32 v240, v240
	v_exp_f32_e32 v241, v241
	v_exp_f32_e32 v242, v242
	v_exp_f32_e32 v243, v243
	v_exp_f32_e32 v244, v244
	v_exp_f32_e32 v245, v245
	v_exp_f32_e32 v246, v246
	v_exp_f32_e32 v247, v247
	v_pk_mul_f32 v[104:105], v[108:109], v[104:105]
	v_pk_mul_f32 v[106:107], v[110:111], v[106:107]
	v_pk_mul_f32 v[96:97], v[100:101], v[96:97]
	v_pk_mul_f32 v[98:99], v[102:103], v[98:99]
	v_pk_add_f32 v[240:241], v[240:241], v[230:231]
	v_pk_add_f32 v[242:243], v[242:243], v[230:231]
	v_pk_add_f32 v[244:245], v[244:245], v[230:231]
	v_pk_add_f32 v[246:247], v[246:247], v[230:231]
	v_rcp_f32_e32 v240, v240
	v_rcp_f32_e32 v241, v241
	v_rcp_f32_e32 v242, v242
	v_rcp_f32_e32 v243, v243
	v_rcp_f32_e32 v244, v244
	v_rcp_f32_e32 v245, v245
	v_rcp_f32_e32 v246, v246
	v_rcp_f32_e32 v247, v247
	v_pk_mul_f32 v[104:105], v[104:105], v[240:241]
	v_pk_mul_f32 v[106:107], v[106:107], v[242:243]
	v_pk_mul_f32 v[96:97], v[96:97], v[244:245]
	v_pk_mul_f32 v[98:99], v[98:99], v[246:247]
	v_cvt_pk_bf16_f32 v232, v104, v105
	v_cvt_pk_bf16_f32 v233, v106, v107
	v_cvt_pk_bf16_f32 v234, v96, v97
	v_cvt_pk_bf16_f32 v235, v98, v99
	global_store_dwordx4 v[236:237], v[232:235], off
	v_or_b32_e32 v238, 32, v154
	v_mad_i64_i32 v[236:237], s[22:23], v238, s44, v[146:147]
	v_pk_mul_f32 v[240:241], v[92:93], v[228:229]
	v_pk_mul_f32 v[242:243], v[94:95], v[228:229]
	v_pk_mul_f32 v[244:245], v[84:85], v[228:229]
	v_pk_mul_f32 v[246:247], v[86:87], v[228:229]
	v_lshl_add_u64 v[236:237], v[236:237], 0, v[144:145]
	v_exp_f32_e32 v240, v240
	v_exp_f32_e32 v241, v241
	v_exp_f32_e32 v242, v242
	v_exp_f32_e32 v243, v243
	v_exp_f32_e32 v244, v244
	v_exp_f32_e32 v245, v245
	v_exp_f32_e32 v246, v246
	v_exp_f32_e32 v247, v247
	v_pk_mul_f32 v[88:89], v[92:93], v[88:89]
	v_pk_mul_f32 v[90:91], v[94:95], v[90:91]
	v_pk_mul_f32 v[80:81], v[84:85], v[80:81]
	v_pk_mul_f32 v[82:83], v[86:87], v[82:83]
	v_pk_add_f32 v[240:241], v[240:241], v[230:231]
	v_pk_add_f32 v[242:243], v[242:243], v[230:231]
	v_pk_add_f32 v[244:245], v[244:245], v[230:231]
	v_pk_add_f32 v[246:247], v[246:247], v[230:231]
	v_rcp_f32_e32 v240, v240
	v_rcp_f32_e32 v241, v241
	v_rcp_f32_e32 v242, v242
	v_rcp_f32_e32 v243, v243
	v_rcp_f32_e32 v244, v244
	v_rcp_f32_e32 v245, v245
	v_rcp_f32_e32 v246, v246
	v_rcp_f32_e32 v247, v247
	v_pk_mul_f32 v[88:89], v[88:89], v[240:241]
	v_pk_mul_f32 v[90:91], v[90:91], v[242:243]
	v_pk_mul_f32 v[80:81], v[80:81], v[244:245]
	v_pk_mul_f32 v[82:83], v[82:83], v[246:247]
	v_cvt_pk_bf16_f32 v232, v88, v89
	v_cvt_pk_bf16_f32 v233, v90, v91
	v_cvt_pk_bf16_f32 v234, v80, v81
	v_cvt_pk_bf16_f32 v235, v82, v83
	global_store_dwordx4 v[236:237], v[232:235], off
	v_or_b32_e32 v238, 48, v154
	v_mad_i64_i32 v[236:237], s[22:23], v238, s44, v[146:147]
	v_pk_mul_f32 v[240:241], v[76:77], v[228:229]
	v_pk_mul_f32 v[242:243], v[78:79], v[228:229]
	v_pk_mul_f32 v[244:245], v[68:69], v[228:229]
	v_pk_mul_f32 v[246:247], v[70:71], v[228:229]
	v_lshl_add_u64 v[236:237], v[236:237], 0, v[144:145]
	v_exp_f32_e32 v240, v240
	v_exp_f32_e32 v241, v241
	v_exp_f32_e32 v242, v242
	v_exp_f32_e32 v243, v243
	v_exp_f32_e32 v244, v244
	v_exp_f32_e32 v245, v245
	v_exp_f32_e32 v246, v246
	v_exp_f32_e32 v247, v247
	v_pk_mul_f32 v[72:73], v[76:77], v[72:73]
	v_pk_mul_f32 v[74:75], v[78:79], v[74:75]
	v_pk_mul_f32 v[64:65], v[68:69], v[64:65]
	v_pk_mul_f32 v[66:67], v[70:71], v[66:67]
	v_pk_add_f32 v[240:241], v[240:241], v[230:231]
	v_pk_add_f32 v[242:243], v[242:243], v[230:231]
	v_pk_add_f32 v[244:245], v[244:245], v[230:231]
; __device__ __forceinline__ unsigned cvt_pk_bf16(float lo, float hi) { unsigned r; asm volatile("v_cvt_pk_bf16_f32 %0, %1, %2" : "=v"(r) : "v"(lo), "v"(hi)); return r; }
; #define PG8_BAR __builtin_amdgcn_s_barrier()
; __device__ __forceinline__ float silu_mul(float g, float u) { return g * u * __builtin_amdgcn_rcpf(1.0f + __builtin_amdgcn_exp2f(-1.4426950408889634f * g)); }
;     __device__ __forceinline__ void operator()(const f32x4 (&acc)[2][2][4][2], const Unit& u, int wr, int wc, int fr, int fq) const {
;         const int row0 = u.pm * BM + wr * 64 + fr, col0 = u.pn * HALF + wc * 32 + 8 * fq;
; #pragma unroll
;         for (int ai = 0; ai < 2; ++ai)
; #pragma unroll
;             for (int m = 0; m < 4; ++m) { bf16_t* rowp = O + (size_t)(row0 + ai * HALF + m * 16) * ldc + col0;
;                 const f32x4 g0 = acc[ai][0][m][0], g1 = acc[ai][0][m][1], u0 = acc[ai][1][m][0], u1 = acc[ai][1][m][1];
;                 u32x4 w; w.x = cvt_pk_bf16(silu_mul(g0[0], u0[0]), silu_mul(g0[1], u0[1])); w.y = cvt_pk_bf16(silu_mul(g0[2], u0[2]), silu_mul(g0[3], u0[3]));
;                 w.z = cvt_pk_bf16(silu_mul(g1[0], u1[0]), silu_mul(g1[1], u1[1])); w.w = cvt_pk_bf16(silu_mul(g1[2], u1[2]), silu_mul(g1[3], u1[3]));
;                 *(u32x4*)rowp = w; }
; template <class Epi, class Sched, bool ALIGN_EPI = false, bool SP2 = false>
; __device__ __forceinline__ void gemm_phase(PG8_LAS unsigned char* lds, const Gemm g, const Sched& S, const Epi& E) {
;     ...
;         if constexpr (ALIGN_EPI) { if (wr == 0) PG8_BAR; }
;         if constexpr (!Epi::AFTER_DRAIN) { E(acc, cur, wr, wc, fr, fq); S.done(cur); }
;         if (!has_next) break;
; #pragma unroll
;         for (int a = 0; a < 2; ++a)
; #pragma unroll
;             for (int b = 0; b < 2; ++b)
; #pragma unroll
;                 for (int m = 0; m < 4; ++m)
; #pragma unroll
;                     for (int n = 0; n < 2; ++n) acc[a][b][m][n] = (f32x4){0.f, 0.f, 0.f, 0.f};
;         cur = nxt; cA = nA; cB = nB; ++ui;
;         if constexpr (ALIGN_EPI) { if (wr == 1) PG8_BAR; }
	v_pk_add_f32 v[246:247], v[246:247], v[230:231]
	v_rcp_f32_e32 v240, v240
	v_rcp_f32_e32 v241, v241
	v_rcp_f32_e32 v242, v242
	v_rcp_f32_e32 v243, v243
	v_rcp_f32_e32 v244, v244
	v_rcp_f32_e32 v245, v245
	v_rcp_f32_e32 v246, v246
	v_rcp_f32_e32 v247, v247
	v_pk_mul_f32 v[72:73], v[72:73], v[240:241]
	v_pk_mul_f32 v[74:75], v[74:75], v[242:243]
	v_pk_mul_f32 v[64:65], v[64:65], v[244:245]
	v_pk_mul_f32 v[66:67], v[66:67], v[246:247]
	v_cvt_pk_bf16_f32 v232, v72, v73
	v_cvt_pk_bf16_f32 v233, v74, v75
	v_cvt_pk_bf16_f32 v234, v64, v65
	v_cvt_pk_bf16_f32 v235, v66, v67
	global_store_dwordx4 v[236:237], v[232:235], off
	v_add_u32_e32 v238, 0x80, v154
	v_mad_i64_i32 v[236:237], s[22:23], v238, s44, v[146:147]
	v_pk_mul_f32 v[240:241], v[60:61], v[228:229]
	v_pk_mul_f32 v[242:243], v[62:63], v[228:229]
	v_pk_mul_f32 v[244:245], v[52:53], v[228:229]
	v_pk_mul_f32 v[246:247], v[54:55], v[228:229]
	v_lshl_add_u64 v[236:237], v[236:237], 0, v[144:145]
	v_exp_f32_e32 v240, v240
	v_exp_f32_e32 v241, v241
	v_exp_f32_e32 v242, v242
	v_exp_f32_e32 v243, v243
	v_exp_f32_e32 v244, v244
	v_exp_f32_e32 v245, v245
	v_exp_f32_e32 v246, v246
	v_exp_f32_e32 v247, v247
	v_pk_mul_f32 v[56:57], v[60:61], v[56:57]
	v_pk_mul_f32 v[58:59], v[62:63], v[58:59]
	v_pk_mul_f32 v[48:49], v[52:53], v[48:49]
	v_pk_mul_f32 v[50:51], v[54:55], v[50:51]
	v_pk_add_f32 v[240:241], v[240:241], v[230:231]
	v_pk_add_f32 v[242:243], v[242:243], v[230:231]
	v_pk_add_f32 v[244:245], v[244:245], v[230:231]
	v_pk_add_f32 v[246:247], v[246:247], v[230:231]
	v_rcp_f32_e32 v240, v240
	v_rcp_f32_e32 v241, v241
	v_rcp_f32_e32 v242, v242
	v_rcp_f32_e32 v243, v243
	v_rcp_f32_e32 v244, v244
	v_rcp_f32_e32 v245, v245
	v_rcp_f32_e32 v246, v246
	v_rcp_f32_e32 v247, v247
	v_pk_mul_f32 v[56:57], v[56:57], v[240:241]
	v_pk_mul_f32 v[58:59], v[58:59], v[242:243]
	v_pk_mul_f32 v[48:49], v[48:49], v[244:245]
	v_pk_mul_f32 v[50:51], v[50:51], v[246:247]
	v_cvt_pk_bf16_f32 v232, v56, v57
	v_cvt_pk_bf16_f32 v233, v58, v59
	v_cvt_pk_bf16_f32 v234, v48, v49
	v_cvt_pk_bf16_f32 v235, v50, v51
	global_store_dwordx4 v[236:237], v[232:235], off
	v_add_u32_e32 v238, 0x90, v154
	v_mad_i64_i32 v[236:237], s[22:23], v238, s44, v[146:147]
	v_pk_mul_f32 v[240:241], v[44:45], v[228:229]
	v_pk_mul_f32 v[242:243], v[46:47], v[228:229]
	v_pk_mul_f32 v[244:245], v[36:37], v[228:229]
	v_pk_mul_f32 v[246:247], v[38:39], v[228:229]
	v_lshl_add_u64 v[236:237], v[236:237], 0, v[144:145]
	v_exp_f32_e32 v240, v240
	v_exp_f32_e32 v241, v241
	v_exp_f32_e32 v242, v242
	v_exp_f32_e32 v243, v243
	v_exp_f32_e32 v244, v244
	v_exp_f32_e32 v245, v245
	v_exp_f32_e32 v246, v246
	v_exp_f32_e32 v247, v247
	v_pk_mul_f32 v[40:41], v[44:45], v[40:41]
	v_pk_mul_f32 v[42:43], v[46:47], v[42:43]
	v_pk_mul_f32 v[32:33], v[36:37], v[32:33]
	v_pk_mul_f32 v[34:35], v[38:39], v[34:35]
	v_pk_add_f32 v[240:241], v[240:241], v[230:231]
	v_pk_add_f32 v[242:243], v[242:243], v[230:231]
	v_pk_add_f32 v[244:245], v[244:245], v[230:231]
	v_pk_add_f32 v[246:247], v[246:247], v[230:231]
	v_rcp_f32_e32 v240, v240
	v_rcp_f32_e32 v241, v241
	v_rcp_f32_e32 v242, v242
	v_rcp_f32_e32 v243, v243
	v_rcp_f32_e32 v244, v244
	v_rcp_f32_e32 v245, v245
	v_rcp_f32_e32 v246, v246
	v_rcp_f32_e32 v247, v247
	v_pk_mul_f32 v[40:41], v[40:41], v[240:241]
	v_pk_mul_f32 v[42:43], v[42:43], v[242:243]
	v_pk_mul_f32 v[32:33], v[32:33], v[244:245]
	v_pk_mul_f32 v[34:35], v[34:35], v[246:247]
	v_cvt_pk_bf16_f32 v232, v40, v41
	v_cvt_pk_bf16_f32 v233, v42, v43
	v_cvt_pk_bf16_f32 v234, v32, v33
	v_cvt_pk_bf16_f32 v235, v34, v35
	global_store_dwordx4 v[236:237], v[232:235], off
	v_add_u32_e32 v238, 0xa0, v154
	v_mad_i64_i32 v[236:237], s[22:23], v238, s44, v[146:147]
	v_pk_mul_f32 v[240:241], v[28:29], v[228:229]
	v_pk_mul_f32 v[242:243], v[30:31], v[228:229]
	v_pk_mul_f32 v[244:245], v[20:21], v[228:229]
	v_pk_mul_f32 v[246:247], v[22:23], v[228:229]
	v_lshl_add_u64 v[236:237], v[236:237], 0, v[144:145]
	v_exp_f32_e32 v240, v240
	v_exp_f32_e32 v241, v241
	v_exp_f32_e32 v242, v242
	v_exp_f32_e32 v243, v243
	v_exp_f32_e32 v244, v244
	v_exp_f32_e32 v245, v245
	v_exp_f32_e32 v246, v246
	v_exp_f32_e32 v247, v247
	v_pk_mul_f32 v[24:25], v[28:29], v[24:25]
	v_pk_mul_f32 v[26:27], v[30:31], v[26:27]
	v_pk_mul_f32 v[16:17], v[20:21], v[16:17]
	v_pk_mul_f32 v[18:19], v[22:23], v[18:19]
	v_pk_add_f32 v[240:241], v[240:241], v[230:231]
	v_pk_add_f32 v[242:243], v[242:243], v[230:231]
	v_pk_add_f32 v[244:245], v[244:245], v[230:231]
	v_pk_add_f32 v[246:247], v[246:247], v[230:231]
	v_rcp_f32_e32 v240, v240
	v_rcp_f32_e32 v241, v241
	v_rcp_f32_e32 v242, v242
	v_rcp_f32_e32 v243, v243
	v_rcp_f32_e32 v244, v244
	v_rcp_f32_e32 v245, v245
	v_rcp_f32_e32 v246, v246
	v_rcp_f32_e32 v247, v247
	v_pk_mul_f32 v[24:25], v[24:25], v[240:241]
	v_pk_mul_f32 v[26:27], v[26:27], v[242:243]
	v_pk_mul_f32 v[16:17], v[16:17], v[244:245]
	v_pk_mul_f32 v[18:19], v[18:19], v[246:247]
	v_cvt_pk_bf16_f32 v232, v24, v25
	v_cvt_pk_bf16_f32 v233, v26, v27
	v_cvt_pk_bf16_f32 v234, v16, v17
	v_cvt_pk_bf16_f32 v235, v18, v19
	global_store_dwordx4 v[236:237], v[232:235], off
	v_add_u32_e32 v238, 0xb0, v154
	v_mad_i64_i32 v[236:237], s[22:23], v238, s44, v[146:147]
	v_pk_mul_f32 v[240:241], v[12:13], v[228:229]
	v_pk_mul_f32 v[242:243], v[14:15], v[228:229]
	v_pk_mul_f32 v[244:245], v[4:5], v[228:229]
	v_pk_mul_f32 v[246:247], v[6:7], v[228:229]
	v_lshl_add_u64 v[236:237], v[236:237], 0, v[144:145]
	v_exp_f32_e32 v240, v240
	v_exp_f32_e32 v241, v241
	v_exp_f32_e32 v242, v242
	v_exp_f32_e32 v243, v243
	v_exp_f32_e32 v244, v244
	v_exp_f32_e32 v245, v245
	v_exp_f32_e32 v246, v246
	v_exp_f32_e32 v247, v247
	v_pk_mul_f32 v[8:9], v[12:13], v[8:9]
	v_pk_mul_f32 v[10:11], v[14:15], v[10:11]
	v_pk_mul_f32 v[0:1], v[4:5], v[0:1]
	v_pk_mul_f32 v[2:3], v[6:7], v[2:3]
	v_pk_add_f32 v[240:241], v[240:241], v[230:231]
	v_pk_add_f32 v[242:243], v[242:243], v[230:231]
	v_pk_add_f32 v[244:245], v[244:245], v[230:231]
	v_pk_add_f32 v[246:247], v[246:247], v[230:231]
	v_rcp_f32_e32 v240, v240
	v_rcp_f32_e32 v241, v241
	v_rcp_f32_e32 v242, v242
	v_rcp_f32_e32 v243, v243
	v_rcp_f32_e32 v244, v244
	v_rcp_f32_e32 v245, v245
	v_rcp_f32_e32 v246, v246
	v_rcp_f32_e32 v247, v247
	v_pk_mul_f32 v[8:9], v[8:9], v[240:241]
	v_pk_mul_f32 v[10:11], v[10:11], v[242:243]
	v_pk_mul_f32 v[0:1], v[0:1], v[244:245]
	v_pk_mul_f32 v[2:3], v[2:3], v[246:247]
	v_cvt_pk_bf16_f32 v232, v8, v9
	v_cvt_pk_bf16_f32 v233, v10, v11
	v_cvt_pk_bf16_f32 v234, v0, v1
	v_cvt_pk_bf16_f32 v235, v2, v3
	global_store_dwordx4 v[236:237], v[232:235], off
	s_andn2_b64 vcc, exec, s[4:5]
	s_mov_b64 s[4:5], -1
	s_cbranch_vccnz .LBB0_1009
	s_andn2_b64 vcc, exec, s[0:1]
	s_cbranch_vccnz .LBB0_1008
	s_barrier
	s_branch .LBB0_1008
